# SGU: gain/bias loads hoisted ahead of stores, no drain after stores; plus S5 fused-FMA scan and saddr up-GEMM
# speedup vs baseline: 1.0067x; 1.0026x over previous
; #define LAS __attribute__((address_space(3)))
; __device__ __forceinline__ void sgu_phase(const Ctx& C, const bf16_t* Z1, const float* VSS, const float* gv, const bf16_t* WSB, const float* bs, bf16_t* Gout) {
;     ...
;         if (C.tid < 128) { const f32x4* p = (const f32x4*)(VSS + (size_t)(tok0 + C.tid) * 32); float s = 0.f;
; #pragma unroll
;             for (int i = 0; i < 8; ++i) { const f32x4 q = p[i]; s += (q[0] + q[1]) + (q[2] + q[3]); }
;             rsv[C.tid] = 1.0f / sqrtf(s * (1.0f / DM) + EPS); }
;         u32x4 vraw[4];
; #pragma unroll
;         for (int ps = 0; ps < 4; ++ps) vraw[ps] = *(const u32x4*)(Z1 + (size_t)(tok0 + ps * 32 + srow) * 4096 + 2048 + 8 * ch);
;         __syncthreads();
;         for (int h = 0; h < 16; ++h) {
;             {
;                 const f32x4 ga = *(const f32x4*)(gv + 128 * h + 8 * ch), gb = *(const f32x4*)(gv + 128 * h + 8 * ch + 4);
; #pragma unroll
;                 for (int ps = 0; ps < 4; ++ps) { const int s = ps * 32 + srow; const u32x4 raw = vraw[ps]; const float r = rsv[s];
;                     u32x4 o; o.x = cvt_pk_bf16(bflo(raw.x) * r * ga[0], bfhi(raw.x) * r * ga[1]); o.y = cvt_pk_bf16(bflo(raw.y) * r * ga[2], bfhi(raw.y) * r * ga[3]);
;                     o.z = cvt_pk_bf16(bflo(raw.z) * r * gb[0], bfhi(raw.z) * r * gb[1]); o.w = cvt_pk_bf16(bflo(raw.w) * r * gb[2], bfhi(raw.w) * r * gb[3]);
;                     *(LAS u32x4*)(Vs + off_b(s, ch)) = o; }
;             }
;             if (h + 1 < 16) {
; #pragma unroll
;                 for (int ps = 0; ps < 4; ++ps) vraw[ps] = *(const u32x4*)(Z1 + (size_t)(tok0 + ps * 32 + srow) * 4096 + 2048 + 128 * (h + 1) + 8 * ch);
;             }
;             bf16x8 wf[4][2];
; #pragma unroll
;             for (int kk = 0; kk < 4; ++kk)
; #pragma unroll
;                 for (int mt = 0; mt < 2; ++mt) wf[kk][mt] = *(const bf16x8*)(WSB + ((size_t)h * 128 + 32 * tb + 16 * mt + fr) * 128 + 32 * (kk <= tb ? kk : tb) + 8 * g4);
;             u32x2 uu[2][4];
; #pragma unroll
;             for (int mt = 0; mt < 2; ++mt)
; #pragma unroll
;                 for (int nt = 0; nt < 4; ++nt) uu[mt][nt] = *(const u32x2*)(Z1 + (size_t)(tok0 + 32 * tb + 16 * mt + fr) * 4096 + 128 * h + 64 * dh + 16 * nt + 4 * g4);
;     ...
; #pragma unroll
;             for (int mt = 0; mt < 2; ++mt) { const int t = 32 * tb + 16 * mt + fr; const float bias = bs[h * 128 + t];
; #pragma unroll
.LBB0_218:
	s_or_b64 exec, exec, s[22:23]
	v_add_u32_e32 v0, s27, v123
	v_ashrrev_i32_e32 v1, 31, v0
	v_readlane_b32 s0, v254, 11
	v_lshlrev_b64 v[2:3], 13, v[0:1]
	v_readlane_b32 s1, v254, 12
	v_add_u32_e32 v4, 32, v0
	v_mov_b32_e32 v139, v65
	v_lshl_add_u64 v[2:3], s[0:1], 0, v[2:3]
	v_ashrrev_i32_e32 v5, 31, v4
	v_lshl_add_u64 v[2:3], v[2:3], 0, v[138:139]
	s_movk_i32 s22, 0x1000
	v_lshlrev_b64 v[4:5], 13, v[4:5]
	v_add_co_u32_e32 v2, vcc, s22, v2
	v_lshl_add_u64 v[4:5], s[0:1], 0, v[4:5]
	s_nop 0
	v_addc_co_u32_e32 v3, vcc, 0, v3, vcc
	v_lshl_add_u64 v[4:5], v[4:5], 0, v[138:139]
	v_add_co_u32_e32 v4, vcc, s22, v4
	v_ashrrev_i32_e32 v115, 31, v114
	s_nop 0
	v_addc_co_u32_e32 v5, vcc, 0, v5, vcc
	global_load_dwordx4 v[12:15], v[2:3], off
	global_load_dwordx4 v[8:11], v[4:5], off
	v_add_u32_e32 v2, 64, v0
	v_ashrrev_i32_e32 v3, 31, v2
	v_lshlrev_b64 v[2:3], 13, v[2:3]
	v_add_u32_e32 v0, 0x60, v0
	v_lshl_add_u64 v[2:3], s[0:1], 0, v[2:3]
	v_ashrrev_i32_e32 v1, 31, v0
	v_lshl_add_u64 v[2:3], v[2:3], 0, v[138:139]
	v_lshlrev_b64 v[0:1], 13, v[0:1]
	v_add_co_u32_e32 v2, vcc, s22, v2
	v_lshl_add_u64 v[0:1], s[0:1], 0, v[0:1]
	s_nop 0
	v_addc_co_u32_e32 v3, vcc, 0, v3, vcc
	v_lshl_add_u64 v[0:1], v[0:1], 0, v[138:139]
	v_add_co_u32_e32 v0, vcc, 0x1000, v0
	v_lshlrev_b64 v[16:17], 13, v[114:115]
	s_nop 0
	v_addc_co_u32_e32 v1, vcc, 0, v1, vcc
	global_load_dwordx4 v[4:7], v[2:3], off
	s_nop 0
	global_load_dwordx4 v[0:3], v[0:1], off
	v_ashrrev_i32_e32 v117, 31, v116
	v_lshl_add_u64 v[142:143], v[112:113], 0, v[16:17]
	v_lshlrev_b64 v[16:17], 13, v[116:117]
	v_ashrrev_i32_e32 v119, 31, v118
	v_lshl_add_u64 v[144:145], v[112:113], 0, v[16:17]
	v_lshlrev_b64 v[16:17], 13, v[118:119]
	v_ashrrev_i32_e32 v121, 31, v120
	v_lshl_add_u64 v[146:147], v[112:113], 0, v[16:17]
	v_lshlrev_b64 v[16:17], 13, v[120:121]
	v_ashrrev_i32_e32 v127, 31, v126
	v_lshl_add_u64 v[148:149], v[112:113], 0, v[16:17]
	v_ashrrev_i32_e32 v125, 31, v124
	v_lshlrev_b64 v[16:17], 13, v[126:127]
	v_lshlrev_b64 v[150:151], 12, v[124:125]
	v_lshlrev_b64 v[152:153], 12, v[126:127]
	v_lshl_add_u64 v[154:155], v[132:133], 0, v[16:17]
	v_lshlrev_b64 v[16:17], 13, v[124:125]
	v_or_b32_e32 v150, v122, v150
	v_or_b32_e32 v152, v122, v152
	v_lshl_add_u64 v[156:157], v[132:133], 0, v[16:17]
	s_mov_b64 s[0:1], 0
	v_mov_b64_e32 v[158:159], v[136:137]
	v_mov_b64_e32 v[160:161], v[134:135]
	v_mov_b64_e32 v[162:163], v[130:131]
	v_mov_b64_e32 v[164:165], v[128:129]
	v_lshl_add_u64 v[16:17], v[80:81], 0, s[0:1]
	global_load_dwordx4 v[72:75], v[16:17], off
	global_load_dwordx4 v[76:79], v[16:17], off offset:16
	s_waitcnt vmcnt(0)
	s_waitcnt lgkmcnt(0)
	s_barrier
	s_branch .LBB0_220
.LBB0_219:
	s_waitcnt vmcnt(9)
	v_lshl_add_u64 v[48:49], v[90:91], 0, s[0:1]
	s_waitcnt vmcnt(8)
	flat_load_dword v52, v[48:49]
	flat_load_dword v70, v[48:49] offset:64
	v_lshl_add_u64 v[50:51], v[80:81], 0, s[0:1]
	global_load_dwordx4 v[72:75], v[50:51], off offset:512
	global_load_dwordx4 v[76:79], v[50:51], off offset:528
	v_lshl_add_u64 v[50:51], s[66:67], 0, v[152:153]
	s_mov_b32 s22, 0x30800000
	s_waitcnt vmcnt(0)
	v_lshlrev_b32_e32 v53, 16, v180
	v_and_b32_e32 v54, 0xffff0000, v180
	v_lshlrev_b32_e32 v55, 16, v181
	v_and_b32_e32 v56, 0xffff0000, v181
	v_lshlrev_b32_e32 v66, 16, v174
	v_and_b32_e32 v67, 0xffff0000, v174
	v_add_co_u32_e32 v50, vcc, s22, v50
	v_lshlrev_b32_e32 v57, 16, v178
	v_and_b32_e32 v58, 0xffff0000, v178
	v_lshlrev_b32_e32 v59, 16, v179
	v_and_b32_e32 v60, 0xffff0000, v179
	v_addc_co_u32_e32 v51, vcc, 0, v51, vcc
	v_lshlrev_b32_e32 v61, 16, v176
	v_and_b32_e32 v62, 0xffff0000, v176
	v_lshlrev_b32_e32 v63, 16, v177
	v_and_b32_e32 v64, 0xffff0000, v177
	v_lshlrev_b32_e32 v68, 16, v175
	v_and_b32_e32 v69, 0xffff0000, v175
	s_mov_b64 vcc, 0x8000
	v_lshl_add_u64 v[164:165], v[164:165], 0, vcc
	v_lshl_add_u64 v[162:163], v[162:163], 0, vcc
	v_lshl_add_u64 v[160:161], v[160:161], 0, vcc
	v_lshl_add_u64 v[158:159], v[158:159], 0, vcc
	s_add_u32 s0, s0, 0x200
	s_mov_b64 s[80:81], 0x100
	s_addc_u32 s1, s1, 0
	v_lshl_add_u64 v[142:143], v[142:143], 0, s[80:81]
	v_lshl_add_u64 v[144:145], v[144:145], 0, s[80:81]
	v_lshl_add_u64 v[146:147], v[146:147], 0, s[80:81]
	v_lshl_add_u64 v[148:149], v[148:149], 0, s[80:81]
	v_lshl_add_u64 v[152:153], v[152:153], 0, s[80:81]
	v_lshl_add_u64 v[154:155], v[154:155], 0, s[80:81]
	s_cmpk_eq_i32 s0, 0x1e00
	v_lshl_add_u64 v[156:157], v[156:157], 0, s[80:81]
	s_waitcnt lgkmcnt(0)
; __device__ __forceinline__ unsigned cvt_pk_bf16(float lo, float hi) { unsigned r; asm volatile("v_cvt_pk_bf16_f32 %0, %1, %2" : "=v"(r) : "v"(lo), "v"(hi)); return r; }
; __device__ __forceinline__ void sgu_phase(const Ctx& C, const bf16_t* Z1, const float* VSS, const float* gv, const bf16_t* WSB, const float* bs, bf16_t* Gout) {
;     ...
; #pragma unroll
;             for (int mt = 0; mt < 2; ++mt) { const int t = 32 * tb + 16 * mt + fr; const float bias = bs[h * 128 + t];
; #pragma unroll
;                 for (int nt = 0; nt < 4; ++nt) { const int d = 128 * h + 64 * dh + 16 * nt + 4 * g4; const u32x2 u2 = uu[mt][nt];
;                     u32x2 o; o.x = cvt_pk_bf16(bflo(u2.x) * (acc[mt][nt][0] + bias), bfhi(u2.x) * (acc[mt][nt][1] + bias)); o.y = cvt_pk_bf16(bflo(u2.y) * (acc[mt][nt][2] + bias), bfhi(u2.y) * (acc[mt][nt][3] + bias));
;                     *(u32x2*)(Gout + (size_t)(tok0 + t) * DM + d) = o; } }
	v_add_f32_e32 v44, v52, v44
	v_add_f32_e32 v45, v52, v45
	v_add_f32_e32 v46, v52, v46
	v_add_f32_e32 v47, v52, v47
	v_add_f32_e32 v32, v32, v52
	v_add_f32_e32 v33, v33, v52
	v_add_f32_e32 v40, v40, v52
	v_add_f32_e32 v41, v41, v52
	v_add_f32_e32 v42, v42, v52
	v_add_f32_e32 v43, v43, v52
	v_add_f32_e32 v36, v36, v52
	v_add_f32_e32 v37, v37, v52
	v_add_f32_e32 v38, v38, v52
	v_add_f32_e32 v39, v39, v52
	v_add_f32_e32 v34, v34, v52
	v_add_f32_e32 v35, v35, v52
	v_mul_f32_e32 v44, v44, v53
	v_mul_f32_e32 v45, v45, v54
	v_mul_f32_e32 v46, v46, v55
	v_mul_f32_e32 v47, v47, v56
	v_mul_f32_e32 v52, v32, v66
	v_mul_f32_e32 v53, v33, v67
	v_cvt_pk_bf16_f32 v32, v44, v45
	v_cvt_pk_bf16_f32 v33, v46, v47
	v_mul_f32_e32 v40, v40, v57
	v_mul_f32_e32 v41, v41, v58
	v_mul_f32_e32 v42, v42, v59
	v_mul_f32_e32 v43, v43, v60
	global_store_dwordx2 v[50:51], v[32:33], off
	v_cvt_pk_bf16_f32 v32, v40, v41
	v_cvt_pk_bf16_f32 v33, v42, v43
	v_mul_f32_e32 v36, v36, v61
	v_mul_f32_e32 v37, v37, v62
	v_mul_f32_e32 v38, v38, v63
	v_mul_f32_e32 v39, v39, v64
	global_store_dwordx2 v[50:51], v[32:33], off offset:32
	v_cvt_pk_bf16_f32 v32, v36, v37
	v_cvt_pk_bf16_f32 v33, v38, v39
	v_mul_f32_e32 v34, v34, v68
	v_mul_f32_e32 v35, v35, v69
	global_store_dwordx2 v[50:51], v[32:33], off offset:64
	v_cvt_pk_bf16_f32 v32, v52, v53
	v_cvt_pk_bf16_f32 v33, v34, v35
	global_store_dwordx2 v[50:51], v[32:33], off offset:96
	v_lshl_add_u64 v[32:33], s[66:67], 0, v[150:151]
	v_lshlrev_b32_e32 v35, 16, v172
	v_and_b32_e32 v36, 0xffff0000, v172
	v_lshlrev_b32_e32 v37, 16, v173
	v_and_b32_e32 v38, 0xffff0000, v173
	v_lshlrev_b32_e32 v47, 16, v166
	v_and_b32_e32 v48, 0xffff0000, v166
	v_add_co_u32_e32 v32, vcc, s22, v32
	v_lshlrev_b32_e32 v39, 16, v170
	v_and_b32_e32 v40, 0xffff0000, v170
	v_lshlrev_b32_e32 v41, 16, v171
	v_and_b32_e32 v42, 0xffff0000, v171
	v_addc_co_u32_e32 v33, vcc, 0, v33, vcc
	v_lshlrev_b32_e32 v43, 16, v168
	v_and_b32_e32 v44, 0xffff0000, v168
	v_lshlrev_b32_e32 v45, 16, v169
	v_and_b32_e32 v46, 0xffff0000, v169
	v_lshlrev_b32_e32 v49, 16, v167
	v_and_b32_e32 v50, 0xffff0000, v167
	v_lshl_add_u64 v[150:151], v[150:151], 0, s[80:81]
	v_add_f32_e32 v28, v28, v70
	v_add_f32_e32 v29, v29, v70
	v_add_f32_e32 v30, v30, v70
	v_add_f32_e32 v31, v31, v70
	v_add_f32_e32 v16, v16, v70
	v_add_f32_e32 v17, v17, v70
	v_add_f32_e32 v24, v24, v70
	v_add_f32_e32 v25, v25, v70
	v_add_f32_e32 v26, v26, v70
	v_add_f32_e32 v27, v27, v70
	v_add_f32_e32 v20, v20, v70
	v_add_f32_e32 v21, v21, v70
	v_add_f32_e32 v22, v22, v70
	v_add_f32_e32 v23, v23, v70
	v_add_f32_e32 v18, v18, v70
	v_add_f32_e32 v19, v19, v70
	v_mul_f32_e32 v28, v28, v35
	v_mul_f32_e32 v29, v29, v36
	v_mul_f32_e32 v30, v30, v37
	v_mul_f32_e32 v31, v31, v38
	v_mul_f32_e32 v34, v16, v47
	v_mul_f32_e32 v35, v17, v48
	v_cvt_pk_bf16_f32 v16, v28, v29
	v_cvt_pk_bf16_f32 v17, v30, v31
	v_mul_f32_e32 v24, v24, v39
	v_mul_f32_e32 v25, v25, v40
	v_mul_f32_e32 v26, v26, v41
	v_mul_f32_e32 v27, v27, v42
	global_store_dwordx2 v[32:33], v[16:17], off
	v_cvt_pk_bf16_f32 v16, v24, v25
	v_cvt_pk_bf16_f32 v17, v26, v27
	v_mul_f32_e32 v20, v20, v43
	v_mul_f32_e32 v21, v21, v44
	v_mul_f32_e32 v22, v22, v45
	v_mul_f32_e32 v23, v23, v46
	global_store_dwordx2 v[32:33], v[16:17], off offset:32
	v_cvt_pk_bf16_f32 v16, v20, v21
	v_cvt_pk_bf16_f32 v17, v22, v23
	v_mul_f32_e32 v18, v18, v49
	v_mul_f32_e32 v19, v19, v50
	global_store_dwordx2 v[32:33], v[16:17], off offset:64
	v_cvt_pk_bf16_f32 v16, v34, v35
	v_cvt_pk_bf16_f32 v17, v18, v19
	global_store_dwordx2 v[32:33], v[16:17], off offset:96
	s_barrier
	s_cbranch_scc1 .LBB0_228
; __device__ __forceinline__ void sgu_phase(const Ctx& C, const bf16_t* Z1, const float* VSS, const float* gv, const bf16_t* WSB, const float* bs, bf16_t* Gout) {
;     ...
;         for (int h = 0; h < 16; ++h) {
;             {
;                 const f32x4 ga = *(const f32x4*)(gv + 128 * h + 8 * ch), gb = *(const f32x4*)(gv + 128 * h + 8 * ch + 4);
; #pragma unroll
;                 for (int ps = 0; ps < 4; ++ps) { const int s = ps * 32 + srow; const u32x4 raw = vraw[ps]; const float r = rsv[s];
;                     u32x4 o; o.x = cvt_pk_bf16(bflo(raw.x) * r * ga[0], bfhi(raw.x) * r * ga[1]); o.y = cvt_pk_bf16(bflo(raw.y) * r * ga[2], bfhi(raw.y) * r * ga[3]);
;                     o.z = cvt_pk_bf16(bflo(raw.z) * r * gb[0], bfhi(raw.z) * r * gb[1]); o.w = cvt_pk_bf16(bflo(raw.w) * r * gb[2], bfhi(raw.w) * r * gb[3]);
;                     *(LAS u32x4*)(Vs + off_b(s, ch)) = o; }
;             }
;             if (h + 1 < 16) {
; #pragma unroll
;                 for (int ps = 0; ps < 4; ++ps) vraw[ps] = *(const u32x4*)(Z1 + (size_t)(tok0 + ps * 32 + srow) * 4096 + 2048 + 128 * (h + 1) + 8 * ch);
;             }
;             bf16x8 wf[4][2];
; #pragma unroll
;             for (int kk = 0; kk < 4; ++kk)
; #pragma unroll
;                 for (int mt = 0; mt < 2; ++mt) wf[kk][mt] = *(const bf16x8*)(WSB + ((size_t)h * 128 + 32 * tb + 16 * mt + fr) * 128 + 32 * (kk <= tb ? kk : tb) + 8 * g4);
;             u32x2 uu[2][4];
; #pragma unroll
;             for (int mt = 0; mt < 2; ++mt)
; #pragma unroll
;                 for (int nt = 0; nt < 4; ++nt) uu[mt][nt] = *(const u32x2*)(Z1 + (size_t)(tok0 + 32 * tb + 16 * mt + fr) * 4096 + 128 * h + 64 * dh + 16 * nt + 4 * g4);
;             __syncthreads();
;             f32x4 acc[2][4];
; #pragma unroll
;             for (int a = 0; a < 2; ++a)
; #pragma unroll
;                 for (int b = 0; b < 4; ++b) acc[a][b] = (f32x4){0.f, 0.f, 0.f, 0.f};
; #pragma unroll
;             for (int kk = 0; kk < 4; ++kk) {
;                 if (kk <= tb) {
;                     unsigned ad[8]; bf16x8 vf[4];
; #pragma unroll
;                     for (int nt = 0; nt < 4; ++nt) { ad[2 * nt] = ldsbase + tr_read_addr_16(lane, 4 * dh + nt, kk, 0); ad[2 * nt + 1] = ldsbase + tr_read_addr_16(lane, 4 * dh + nt, kk, 1); }
;                     tr_read8(vf, ad);
; #pragma unroll
;                     for (int nt = 0; nt < 4; ++nt)
; #pragma unroll
.LBB0_220:
	v_mov_b64_e32 v[20:21], v[72:73]
	v_mov_b64_e32 v[22:23], v[74:75]
	v_mov_b64_e32 v[16:17], v[76:77]
	v_mov_b64_e32 v[18:19], v[78:79]
	ds_read_b32 v24, v183 offset:32768
	v_lshlrev_b32_e32 v25, 16, v12
	v_and_b32_e32 v12, 0xffff0000, v12
	v_add_u32_e32 v115, v182, v184
	s_mov_b32 s22, 0x1f01000
	s_waitcnt lgkmcnt(0)
	v_mul_f32_e32 v25, v24, v25
	v_mul_f32_e32 v12, v24, v12
	v_mul_f32_e32 v25, v20, v25
	v_mul_f32_e32 v12, v21, v12
	v_cvt_pk_bf16_f32 v12, v25, v12
	v_lshlrev_b32_e32 v25, 16, v13
	v_and_b32_e32 v13, 0xffff0000, v13
	v_mul_f32_e32 v25, v24, v25
	v_mul_f32_e32 v13, v24, v13
	v_mul_f32_e32 v25, v22, v25
	v_mul_f32_e32 v13, v23, v13
	v_cvt_pk_bf16_f32 v13, v25, v13
	v_lshlrev_b32_e32 v25, 16, v14
	v_and_b32_e32 v14, 0xffff0000, v14
	v_mul_f32_e32 v25, v24, v25
	v_mul_f32_e32 v14, v24, v14
	v_mul_f32_e32 v25, v16, v25
	v_mul_f32_e32 v14, v17, v14
	v_cvt_pk_bf16_f32 v14, v25, v14
	v_lshlrev_b32_e32 v25, 16, v15
	v_and_b32_e32 v15, 0xffff0000, v15
	v_mul_f32_e32 v15, v24, v15
	v_mul_f32_e32 v25, v24, v25
	v_mul_f32_e32 v15, v19, v15
	v_mul_f32_e32 v25, v18, v25
	v_cvt_pk_bf16_f32 v15, v25, v15
	ds_write_b128 v115, v[12:15]
	ds_read_b32 v12, v183 offset:32896
	v_lshlrev_b32_e32 v13, 16, v8
	v_and_b32_e32 v8, 0xffff0000, v8
	s_waitcnt lgkmcnt(0)
	v_mul_f32_e32 v13, v12, v13
	v_mul_f32_e32 v8, v12, v8
	v_mul_f32_e32 v13, v20, v13
	v_mul_f32_e32 v8, v21, v8
	v_cvt_pk_bf16_f32 v8, v13, v8
	v_lshlrev_b32_e32 v13, 16, v9
	v_and_b32_e32 v9, 0xffff0000, v9
	v_mul_f32_e32 v13, v12, v13
	v_mul_f32_e32 v9, v12, v9
	v_mul_f32_e32 v13, v22, v13
	v_mul_f32_e32 v9, v23, v9
	v_cvt_pk_bf16_f32 v9, v13, v9
	v_lshlrev_b32_e32 v13, 16, v10
	v_and_b32_e32 v10, 0xffff0000, v10
	v_mul_f32_e32 v13, v12, v13
	v_mul_f32_e32 v10, v12, v10
	v_mul_f32_e32 v13, v16, v13
	v_mul_f32_e32 v10, v17, v10
	v_cvt_pk_bf16_f32 v10, v13, v10
	v_lshlrev_b32_e32 v13, 16, v11
	v_and_b32_e32 v11, 0xffff0000, v11
	v_mul_f32_e32 v11, v12, v11
	v_mul_f32_e32 v13, v12, v13
	v_mul_f32_e32 v11, v19, v11
	v_mul_f32_e32 v13, v18, v13
	v_cvt_pk_bf16_f32 v11, v13, v11
	ds_write_b128 v230, v[8:11]
	ds_read_b32 v8, v183 offset:33024
	v_lshlrev_b32_e32 v9, 16, v4
	v_and_b32_e32 v4, 0xffff0000, v4
	s_waitcnt lgkmcnt(0)
	v_mul_f32_e32 v9, v8, v9
	v_mul_f32_e32 v4, v8, v4
	v_mul_f32_e32 v9, v20, v9
	v_mul_f32_e32 v4, v21, v4
	v_cvt_pk_bf16_f32 v4, v9, v4
	v_lshlrev_b32_e32 v9, 16, v5
	v_and_b32_e32 v5, 0xffff0000, v5
	v_mul_f32_e32 v9, v8, v9
	v_mul_f32_e32 v5, v8, v5
	v_mul_f32_e32 v9, v22, v9
	v_mul_f32_e32 v5, v23, v5
	v_cvt_pk_bf16_f32 v5, v9, v5
	v_lshlrev_b32_e32 v9, 16, v6
	v_and_b32_e32 v6, 0xffff0000, v6
	v_mul_f32_e32 v9, v8, v9
	v_mul_f32_e32 v6, v8, v6
	v_mul_f32_e32 v9, v16, v9
	v_mul_f32_e32 v6, v17, v6
	v_cvt_pk_bf16_f32 v6, v9, v6
	v_lshlrev_b32_e32 v9, 16, v7
	v_and_b32_e32 v7, 0xffff0000, v7
	v_mul_f32_e32 v7, v8, v7
	v_mul_f32_e32 v9, v8, v9
	v_mul_f32_e32 v7, v19, v7
	v_mul_f32_e32 v9, v18, v9
	v_cvt_pk_bf16_f32 v7, v9, v7
	ds_write_b128 v231, v[4:7]
	ds_read_b32 v4, v183 offset:33152
	v_lshlrev_b32_e32 v5, 16, v0
	v_and_b32_e32 v0, 0xffff0000, v0
	s_waitcnt lgkmcnt(0)
	v_mul_f32_e32 v5, v4, v5
	v_mul_f32_e32 v0, v4, v0
	v_mul_f32_e32 v5, v20, v5
	v_mul_f32_e32 v0, v21, v0
	v_cvt_pk_bf16_f32 v0, v5, v0
	v_lshlrev_b32_e32 v5, 16, v1
	v_and_b32_e32 v1, 0xffff0000, v1
	v_mul_f32_e32 v5, v4, v5
	v_mul_f32_e32 v1, v4, v1
	v_mul_f32_e32 v5, v22, v5
	v_mul_f32_e32 v1, v23, v1
	v_cvt_pk_bf16_f32 v1, v5, v1
	v_lshlrev_b32_e32 v5, 16, v2
	v_and_b32_e32 v2, 0xffff0000, v2
	v_mul_f32_e32 v5, v4, v5
	v_mul_f32_e32 v2, v4, v2
	v_mul_f32_e32 v5, v16, v5
	v_mul_f32_e32 v2, v17, v2
	v_cvt_pk_bf16_f32 v2, v5, v2
	v_lshlrev_b32_e32 v5, 16, v3
	v_and_b32_e32 v3, 0xffff0000, v3
	v_mul_f32_e32 v3, v4, v3
	v_mul_f32_e32 v5, v4, v5
	v_mul_f32_e32 v3, v19, v3
	v_mul_f32_e32 v5, v18, v5
	v_cvt_pk_bf16_f32 v3, v5, v3
	ds_write_b128 v232, v[0:3]
	v_lshl_add_u64 v[0:1], s[66:67], 0, v[142:143]
	global_load_dwordx4 v[12:15], v[0:1], off
	v_lshl_add_u64 v[0:1], s[66:67], 0, v[144:145]
	v_lshl_add_u64 v[16:17], s[66:67], 0, v[158:159]
	global_load_dwordx4 v[8:11], v[0:1], off
	v_lshl_add_u64 v[0:1], s[66:67], 0, v[146:147]
	v_add_co_u32_e32 v20, vcc, s22, v16
	global_load_dwordx4 v[4:7], v[0:1], off
	v_lshl_add_u64 v[0:1], s[66:67], 0, v[148:149]
	v_addc_co_u32_e32 v21, vcc, 0, v17, vcc
	global_load_dwordx4 v[0:3], v[0:1], off
	s_nop 0
	global_load_dwordx4 v[16:19], v[20:21], off offset:-4096
	global_load_dwordx4 v[76:79], v[20:21], off
	v_lshl_add_u64 v[20:21], s[66:67], 0, v[160:161]
	v_add_co_u32_e32 v20, vcc, s22, v20
	s_nop 1
	v_addc_co_u32_e32 v21, vcc, 0, v21, vcc
	global_load_dwordx4 v[68:71], v[20:21], off offset:-4096
	global_load_dwordx4 v[72:75], v[20:21], off
	v_lshl_add_u64 v[20:21], s[66:67], 0, v[162:163]
	v_add_co_u32_e32 v20, vcc, s22, v20
	s_nop 1
	v_addc_co_u32_e32 v21, vcc, 0, v21, vcc
	global_load_dwordx4 v[56:59], v[20:21], off offset:-4096
	global_load_dwordx4 v[60:63], v[20:21], off
	v_lshl_add_u64 v[20:21], s[66:67], 0, v[164:165]
	v_add_co_u32_e32 v20, vcc, s22, v20
	s_nop 1
	v_addc_co_u32_e32 v21, vcc, 0, v21, vcc
	global_load_dwordx4 v[48:51], v[20:21], off offset:-4096
	global_load_dwordx4 v[52:55], v[20:21], off
	v_lshl_add_u64 v[20:21], s[66:67], 0, v[154:155]
	global_load_dwordx2 v[180:181], v[20:21], off offset:-64
	global_load_dwordx2 v[178:179], v[20:21], off offset:-32
	global_load_dwordx2 v[176:177], v[20:21], off
	global_load_dwordx2 v[174:175], v[20:21], off offset:32
	v_lshl_add_u64 v[20:21], s[66:67], 0, v[156:157]
	global_load_dwordx2 v[172:173], v[20:21], off offset:-64
	global_load_dwordx2 v[170:171], v[20:21], off offset:-32
	global_load_dwordx2 v[168:169], v[20:21], off
	global_load_dwordx2 v[166:167], v[20:21], off offset:32
	v_cndmask_b32_e64 v20, 0, 1, s[54:55]
	v_cmp_ne_u32_e64 s[40:41], 1, v20
	s_andn2_b64 vcc, exec, s[54:55]
	s_waitcnt lgkmcnt(0)
	s_barrier
	s_cbranch_vccnz .LBB0_222
	ds_read_b64_tr_b16 v[28:29], v185
	ds_read_b64_tr_b16 v[30:31], v186
	ds_read_b64_tr_b16 v[24:25], v187
	ds_read_b64_tr_b16 v[26:27], v188
	ds_read_b64_tr_b16 v[20:21], v189
	ds_read_b64_tr_b16 v[22:23], v190
	ds_read_b64_tr_b16 v[234:235], v191
	ds_read_b64_tr_b16 v[236:237], v192
	s_waitcnt lgkmcnt(0)
	s_waitcnt vmcnt(15)
	v_mfma_f32_16x16x32_bf16 v[44:47], v[28:31], v[16:19], 0
	s_waitcnt vmcnt(14)
	v_mfma_f32_16x16x32_bf16 v[28:31], v[28:31], v[76:79], 0
	v_mfma_f32_16x16x32_bf16 v[40:43], v[24:27], v[16:19], 0
	v_mfma_f32_16x16x32_bf16 v[24:27], v[24:27], v[76:79], 0
	v_mfma_f32_16x16x32_bf16 v[36:39], v[20:23], v[16:19], 0
	v_mfma_f32_16x16x32_bf16 v[20:23], v[20:23], v[76:79], 0
	v_mfma_f32_16x16x32_bf16 v[32:35], v[234:237], v[16:19], 0
	v_mfma_f32_16x16x32_bf16 v[16:19], v[234:237], v[76:79], 0
	v_cndmask_b32_e64 v64, 0, 1, s[56:57]
	v_cmp_ne_u32_e64 s[42:43], 1, v64
	s_andn2_b64 vcc, exec, s[56:57]
	s_cbranch_vccz .LBB0_223
	s_branch .LBB0_224
